# adds: same first-iteration peel on the in1 GEMM site (128 zero moves per tile gone)
# baseline (speedup 1.0000x reference)
.LBB0_1141:
	s_add_u32 s0, s6, 0x80
	s_addc_u32 s1, s7, 0
	s_add_u32 s6, s4, 0x100
	s_addc_u32 s7, s5, 0
	s_mov_b32 s4, 0
	s_add_i32 s9, s4, 2
	s_add_u32 s10, s0, 0x80
	s_addc_u32 s5, s1, 0
	s_add_i32 s31, 0, 0x10000
	s_cmp_eq_u32 s77, s4
	s_cselect_b32 s5, s23, s5
	s_cselect_b32 s4, s22, s10
	v_add_u32_e32 v1, s31, v165
	s_cselect_b32 s11, s67, s7
	s_cselect_b32 s10, s66, s6
	s_add_i32 s53, 0, 0x14000
	ds_read_b128 v[82:85], v1
	ds_read_b128 v[86:89], v1 offset:1024
	ds_read_b128 v[138:141], v1 offset:2048
	ds_read_b128 v[142:145], v1 offset:3072
	v_add_u32_e32 v1, s53, v165
	ds_read_b128 v[158:161], v1
	ds_read_b128 v[168:171], v1 offset:1024
	ds_read_b128 v[172:175], v1 offset:2048
	ds_read_b128 v[176:179], v1 offset:3072
	v_lshl_add_u64 v[162:163], s[0:1], 0, v[154:155]
	s_add_i32 m0, s70, 0xc000
	ds_read_b128 v[180:183], v167
	ds_read_b128 v[184:187], v167 offset:1024
	ds_read_b128 v[188:191], v167 offset:2048
	ds_read_b128 v[192:195], v167 offset:3072
	ds_read_b128 v[196:199], v167 offset:4096
	ds_read_b128 v[200:203], v167 offset:5120
	ds_read_b128 v[214:217], v167 offset:6144
	ds_read_b128 v[218:221], v167 offset:7168
	global_load_lds_dwordx4 v[162:163], off
	v_lshl_add_u64 v[162:163], s[0:1], 0, v[156:157]
	s_add_i32 m0, s70, 0xe000
	s_nop 0
	global_load_lds_dwordx4 v[162:163], off
	s_waitcnt vmcnt(8)
	s_waitcnt lgkmcnt(0)
	s_barrier
	s_setprio 1
	s_waitcnt lgkmcnt(0)
	v_mfma_f32_16x16x32_bf16 v[134:137], v[82:85], v[180:183], 0
	v_mfma_f32_16x16x32_bf16 v[130:133], v[138:141], v[180:183], 0
	v_mfma_f32_16x16x32_bf16 v[126:129], v[82:85], v[188:191], 0
	v_mfma_f32_16x16x32_bf16 v[122:125], v[138:141], v[188:191], 0
	v_mfma_f32_16x16x32_bf16 v[118:121], v[82:85], v[196:199], 0
	v_mfma_f32_16x16x32_bf16 v[114:117], v[138:141], v[196:199], 0
	v_mfma_f32_16x16x32_bf16 v[110:113], v[82:85], v[214:217], 0
	v_mfma_f32_16x16x32_bf16 v[106:109], v[138:141], v[214:217], 0
	v_mfma_f32_16x16x32_bf16 v[134:137], v[86:89], v[184:187], v[134:137]
	v_mfma_f32_16x16x32_bf16 v[130:133], v[142:145], v[184:187], v[130:133]
	v_mfma_f32_16x16x32_bf16 v[126:129], v[86:89], v[192:195], v[126:129]
	v_mfma_f32_16x16x32_bf16 v[122:125], v[142:145], v[192:195], v[122:125]
	v_mfma_f32_16x16x32_bf16 v[118:121], v[86:89], v[200:203], v[118:121]
	v_mfma_f32_16x16x32_bf16 v[114:117], v[142:145], v[200:203], v[114:117]
	v_mfma_f32_16x16x32_bf16 v[110:113], v[86:89], v[218:221], v[110:113]
	v_mfma_f32_16x16x32_bf16 v[106:109], v[142:145], v[218:221], v[106:109]
	s_setprio 0
	s_setprio 1
	v_mfma_f32_16x16x32_bf16 v[62:65], v[158:161], v[180:183], 0
	v_mfma_f32_16x16x32_bf16 v[58:61], v[172:175], v[180:183], 0
	v_mfma_f32_16x16x32_bf16 v[54:57], v[158:161], v[188:191], 0
	v_mfma_f32_16x16x32_bf16 v[50:53], v[172:175], v[188:191], 0
	v_mfma_f32_16x16x32_bf16 v[46:49], v[158:161], v[196:199], 0
	v_mfma_f32_16x16x32_bf16 v[42:45], v[172:175], v[196:199], 0
	v_mfma_f32_16x16x32_bf16 v[38:41], v[158:161], v[214:217], 0
	v_mfma_f32_16x16x32_bf16 v[34:37], v[172:175], v[214:217], 0
	v_mfma_f32_16x16x32_bf16 v[62:65], v[168:171], v[184:187], v[62:65]
	v_mfma_f32_16x16x32_bf16 v[58:61], v[176:179], v[184:187], v[58:61]
	v_mfma_f32_16x16x32_bf16 v[54:57], v[168:171], v[192:195], v[54:57]
	v_mfma_f32_16x16x32_bf16 v[50:53], v[176:179], v[192:195], v[50:53]
	v_mfma_f32_16x16x32_bf16 v[46:49], v[168:171], v[200:203], v[46:49]
	v_mfma_f32_16x16x32_bf16 v[42:45], v[176:179], v[200:203], v[42:45]
	v_mfma_f32_16x16x32_bf16 v[38:41], v[168:171], v[218:221], v[38:41]
	v_mfma_f32_16x16x32_bf16 v[34:37], v[176:179], v[218:221], v[34:37]
	s_setprio 0
	s_barrier
	s_add_i32 s31, s31, s65
	v_lshl_add_u64 v[162:163], s[10:11], 0, v[150:151]
	s_mov_b32 m0, s31
	ds_read_b128 v[180:183], v167 offset:16384
	ds_read_b128 v[184:187], v167 offset:17408
	ds_read_b128 v[188:191], v167 offset:18432
	ds_read_b128 v[192:195], v167 offset:19456
	ds_read_b128 v[196:199], v167 offset:20480
	ds_read_b128 v[200:203], v167 offset:21504
	ds_read_b128 v[214:217], v167 offset:22528
	ds_read_b128 v[218:221], v167 offset:23552
	global_load_lds_dwordx4 v[162:163], off
	s_add_i32 m0, s31, 0x2000
	v_lshl_add_u64 v[204:205], s[10:11], 0, v[146:147]
	s_add_u32 s10, s10, s12
	s_addc_u32 s11, s11, s13
	s_add_i32 s31, s53, s65
	global_load_lds_dwordx4 v[204:205], off
	v_lshl_add_u64 v[222:223], s[10:11], 0, v[150:151]
	s_mov_b32 m0, s31
	v_lshl_add_u64 v[224:225], s[10:11], 0, v[146:147]
	global_load_lds_dwordx4 v[222:223], off
	s_add_i32 m0, s31, 0x2000
	v_lshl_add_u64 v[226:227], s[4:5], 0, v[152:153]
	global_load_lds_dwordx4 v[224:225], off
	s_mov_b32 m0, s70
	v_lshl_add_u64 v[236:237], s[4:5], 0, v[148:149]
	global_load_lds_dwordx4 v[226:227], off
	s_mov_b32 m0, s71
	s_nop 0
	global_load_lds_dwordx4 v[236:237], off
	s_waitcnt vmcnt(8)
	s_waitcnt lgkmcnt(0)
	s_barrier
	s_setprio 1
	s_waitcnt lgkmcnt(0)
	v_mfma_f32_16x16x32_bf16 v[102:105], v[82:85], v[180:183], 0
	v_mfma_f32_16x16x32_bf16 v[98:101], v[138:141], v[180:183], 0
	v_mfma_f32_16x16x32_bf16 v[94:97], v[82:85], v[188:191], 0
	v_mfma_f32_16x16x32_bf16 v[90:93], v[138:141], v[188:191], 0
	v_mfma_f32_16x16x32_bf16 v[78:81], v[82:85], v[196:199], 0
	v_mfma_f32_16x16x32_bf16 v[74:77], v[138:141], v[196:199], 0
	v_mfma_f32_16x16x32_bf16 v[70:73], v[82:85], v[214:217], 0
	v_mfma_f32_16x16x32_bf16 v[66:69], v[138:141], v[214:217], 0
	v_mfma_f32_16x16x32_bf16 v[102:105], v[86:89], v[184:187], v[102:105]
	v_mfma_f32_16x16x32_bf16 v[98:101], v[142:145], v[184:187], v[98:101]
	v_mfma_f32_16x16x32_bf16 v[94:97], v[86:89], v[192:195], v[94:97]
	v_mfma_f32_16x16x32_bf16 v[90:93], v[142:145], v[192:195], v[90:93]
	v_mfma_f32_16x16x32_bf16 v[78:81], v[86:89], v[200:203], v[78:81]
	v_mfma_f32_16x16x32_bf16 v[74:77], v[142:145], v[200:203], v[74:77]
	v_mfma_f32_16x16x32_bf16 v[70:73], v[86:89], v[218:221], v[70:73]
	v_mfma_f32_16x16x32_bf16 v[66:69], v[142:145], v[218:221], v[66:69]
	s_setprio 0
	s_setprio 1
	v_mfma_f32_16x16x32_bf16 v[30:33], v[158:161], v[180:183], 0
	v_mfma_f32_16x16x32_bf16 v[26:29], v[172:175], v[180:183], 0
	v_mfma_f32_16x16x32_bf16 v[22:25], v[158:161], v[188:191], 0
	v_mfma_f32_16x16x32_bf16 v[18:21], v[172:175], v[188:191], 0
	v_mfma_f32_16x16x32_bf16 v[14:17], v[158:161], v[196:199], 0
	v_mfma_f32_16x16x32_bf16 v[10:13], v[172:175], v[196:199], 0
	v_mfma_f32_16x16x32_bf16 v[6:9], v[158:161], v[214:217], 0
	v_mfma_f32_16x16x32_bf16 v[2:5], v[172:175], v[214:217], 0
	v_mfma_f32_16x16x32_bf16 v[30:33], v[168:171], v[184:187], v[30:33]
	v_mfma_f32_16x16x32_bf16 v[26:29], v[176:179], v[184:187], v[26:29]
	v_mfma_f32_16x16x32_bf16 v[22:25], v[168:171], v[192:195], v[22:25]
	v_mfma_f32_16x16x32_bf16 v[18:21], v[176:179], v[192:195], v[18:21]
	v_mfma_f32_16x16x32_bf16 v[14:17], v[168:171], v[200:203], v[14:17]
	v_mfma_f32_16x16x32_bf16 v[10:13], v[176:179], v[200:203], v[10:13]
	v_mfma_f32_16x16x32_bf16 v[6:9], v[168:171], v[218:221], v[6:9]
	v_mfma_f32_16x16x32_bf16 v[2:5], v[176:179], v[218:221], v[2:5]
	s_setprio 0
	s_barrier
	s_add_i32 s10, 0, 0x18000
	v_add_u32_e32 v1, s10, v165
	s_add_i32 s11, 0, 0x1c000
	ds_read_b128 v[82:85], v1
	ds_read_b128 v[86:89], v1 offset:1024
	ds_read_b128 v[138:141], v1 offset:2048
	ds_read_b128 v[142:145], v1 offset:3072
	v_add_u32_e32 v1, s11, v165
	ds_read_b128 v[158:161], v1
	ds_read_b128 v[168:171], v1 offset:1024
	ds_read_b128 v[172:175], v1 offset:2048
	ds_read_b128 v[176:179], v1 offset:3072
	s_add_u32 s4, s4, s12
	s_addc_u32 s5, s5, s13
	s_mov_b32 m0, s72
	v_lshl_add_u64 v[238:239], s[4:5], 0, v[152:153]
	ds_read_b128 v[180:183], v167 offset:32768
	ds_read_b128 v[184:187], v167 offset:33792
	ds_read_b128 v[188:191], v167 offset:34816
	ds_read_b128 v[192:195], v167 offset:35840
	ds_read_b128 v[196:199], v167 offset:36864
	ds_read_b128 v[200:203], v167 offset:37888
	ds_read_b128 v[214:217], v167 offset:38912
	ds_read_b128 v[218:221], v167 offset:39936
	global_load_lds_dwordx4 v[238:239], off
	v_lshl_add_u64 v[238:239], s[4:5], 0, v[148:149]
	s_mov_b32 m0, s73
	s_nop 0
	global_load_lds_dwordx4 v[238:239], off
	s_waitcnt vmcnt(8)
	s_waitcnt lgkmcnt(0)
	s_barrier
	s_setprio 1
	s_waitcnt lgkmcnt(0)
	v_mfma_f32_16x16x32_bf16 v[134:137], v[82:85], v[180:183], v[134:137]
	v_mfma_f32_16x16x32_bf16 v[130:133], v[138:141], v[180:183], v[130:133]
	v_mfma_f32_16x16x32_bf16 v[126:129], v[82:85], v[188:191], v[126:129]
	v_mfma_f32_16x16x32_bf16 v[122:125], v[138:141], v[188:191], v[122:125]
	v_mfma_f32_16x16x32_bf16 v[118:121], v[82:85], v[196:199], v[118:121]
	v_mfma_f32_16x16x32_bf16 v[114:117], v[138:141], v[196:199], v[114:117]
	v_mfma_f32_16x16x32_bf16 v[110:113], v[82:85], v[214:217], v[110:113]
	v_mfma_f32_16x16x32_bf16 v[106:109], v[138:141], v[214:217], v[106:109]
	v_mfma_f32_16x16x32_bf16 v[134:137], v[86:89], v[184:187], v[134:137]
	v_mfma_f32_16x16x32_bf16 v[130:133], v[142:145], v[184:187], v[130:133]
	v_mfma_f32_16x16x32_bf16 v[126:129], v[86:89], v[192:195], v[126:129]
	v_mfma_f32_16x16x32_bf16 v[122:125], v[142:145], v[192:195], v[122:125]
	v_mfma_f32_16x16x32_bf16 v[118:121], v[86:89], v[200:203], v[118:121]
	v_mfma_f32_16x16x32_bf16 v[114:117], v[142:145], v[200:203], v[114:117]
	v_mfma_f32_16x16x32_bf16 v[110:113], v[86:89], v[218:221], v[110:113]
	v_mfma_f32_16x16x32_bf16 v[106:109], v[142:145], v[218:221], v[106:109]
	s_setprio 0
	s_setprio 1
	v_mfma_f32_16x16x32_bf16 v[62:65], v[158:161], v[180:183], v[62:65]
	v_mfma_f32_16x16x32_bf16 v[58:61], v[172:175], v[180:183], v[58:61]
	v_mfma_f32_16x16x32_bf16 v[54:57], v[158:161], v[188:191], v[54:57]
	v_mfma_f32_16x16x32_bf16 v[50:53], v[172:175], v[188:191], v[50:53]
	v_mfma_f32_16x16x32_bf16 v[46:49], v[158:161], v[196:199], v[46:49]
	v_mfma_f32_16x16x32_bf16 v[42:45], v[172:175], v[196:199], v[42:45]
	v_mfma_f32_16x16x32_bf16 v[38:41], v[158:161], v[214:217], v[38:41]
	v_mfma_f32_16x16x32_bf16 v[34:37], v[172:175], v[214:217], v[34:37]
	v_mfma_f32_16x16x32_bf16 v[62:65], v[168:171], v[184:187], v[62:65]
	v_mfma_f32_16x16x32_bf16 v[58:61], v[176:179], v[184:187], v[58:61]
	v_mfma_f32_16x16x32_bf16 v[54:57], v[168:171], v[192:195], v[54:57]
	v_mfma_f32_16x16x32_bf16 v[50:53], v[176:179], v[192:195], v[50:53]
	v_mfma_f32_16x16x32_bf16 v[46:49], v[168:171], v[200:203], v[46:49]
	v_mfma_f32_16x16x32_bf16 v[42:45], v[176:179], v[200:203], v[42:45]
	v_mfma_f32_16x16x32_bf16 v[38:41], v[168:171], v[218:221], v[38:41]
	v_mfma_f32_16x16x32_bf16 v[34:37], v[176:179], v[218:221], v[34:37]
	s_setprio 0
	s_barrier
	s_add_i32 s4, s10, s65
	v_lshl_add_u64 v[162:163], v[162:163], 0, s[60:61]
	s_mov_b32 m0, s4
	ds_read_b128 v[180:183], v167 offset:49152
	ds_read_b128 v[184:187], v167 offset:50176
	ds_read_b128 v[188:191], v167 offset:51200
	ds_read_b128 v[192:195], v167 offset:52224
	ds_read_b128 v[196:199], v167 offset:53248
	ds_read_b128 v[200:203], v167 offset:54272
	ds_read_b128 v[214:217], v167 offset:55296
	ds_read_b128 v[218:221], v167 offset:56320
	global_load_lds_dwordx4 v[162:163], off
	v_lshl_add_u64 v[162:163], v[204:205], 0, s[60:61]
	s_add_i32 m0, s4, 0x2000
	s_add_i32 s4, s11, s65
	global_load_lds_dwordx4 v[162:163], off
	v_lshl_add_u64 v[162:163], v[222:223], 0, s[60:61]
	s_mov_b32 m0, s4
	s_nop 0
	global_load_lds_dwordx4 v[162:163], off
	v_lshl_add_u64 v[162:163], v[224:225], 0, s[60:61]
	s_add_i32 m0, s4, 0x2000
	s_nop 0
	global_load_lds_dwordx4 v[162:163], off
	v_lshl_add_u64 v[162:163], v[226:227], 0, s[60:61]
	s_mov_b32 m0, s74
	s_nop 0
	global_load_lds_dwordx4 v[162:163], off
	v_lshl_add_u64 v[162:163], v[236:237], 0, s[60:61]
	s_mov_b32 m0, s75
	s_nop 0
	global_load_lds_dwordx4 v[162:163], off
	s_waitcnt vmcnt(8)
	s_waitcnt lgkmcnt(0)
	s_barrier
	s_setprio 1
	s_waitcnt lgkmcnt(0)
	v_mfma_f32_16x16x32_bf16 v[102:105], v[82:85], v[180:183], v[102:105]
	v_mfma_f32_16x16x32_bf16 v[98:101], v[138:141], v[180:183], v[98:101]
	v_mfma_f32_16x16x32_bf16 v[94:97], v[82:85], v[188:191], v[94:97]
	v_mfma_f32_16x16x32_bf16 v[90:93], v[138:141], v[188:191], v[90:93]
	v_mfma_f32_16x16x32_bf16 v[78:81], v[82:85], v[196:199], v[78:81]
	v_mfma_f32_16x16x32_bf16 v[74:77], v[138:141], v[196:199], v[74:77]
	v_mfma_f32_16x16x32_bf16 v[70:73], v[82:85], v[214:217], v[70:73]
	v_mfma_f32_16x16x32_bf16 v[66:69], v[138:141], v[214:217], v[66:69]
	v_mfma_f32_16x16x32_bf16 v[102:105], v[86:89], v[184:187], v[102:105]
	v_mfma_f32_16x16x32_bf16 v[98:101], v[142:145], v[184:187], v[98:101]
	v_mfma_f32_16x16x32_bf16 v[94:97], v[86:89], v[192:195], v[94:97]
	v_mfma_f32_16x16x32_bf16 v[90:93], v[142:145], v[192:195], v[90:93]
	v_mfma_f32_16x16x32_bf16 v[78:81], v[86:89], v[200:203], v[78:81]
	v_mfma_f32_16x16x32_bf16 v[74:77], v[142:145], v[200:203], v[74:77]
	v_mfma_f32_16x16x32_bf16 v[70:73], v[86:89], v[218:221], v[70:73]
	v_mfma_f32_16x16x32_bf16 v[66:69], v[142:145], v[218:221], v[66:69]
	s_setprio 0
	s_setprio 1
	v_mfma_f32_16x16x32_bf16 v[30:33], v[158:161], v[180:183], v[30:33]
	v_mfma_f32_16x16x32_bf16 v[26:29], v[172:175], v[180:183], v[26:29]
	v_mfma_f32_16x16x32_bf16 v[22:25], v[158:161], v[188:191], v[22:25]
	v_mfma_f32_16x16x32_bf16 v[18:21], v[172:175], v[188:191], v[18:21]
	v_mfma_f32_16x16x32_bf16 v[14:17], v[158:161], v[196:199], v[14:17]
	v_mfma_f32_16x16x32_bf16 v[10:13], v[172:175], v[196:199], v[10:13]
	v_mfma_f32_16x16x32_bf16 v[6:9], v[158:161], v[214:217], v[6:9]
	v_mfma_f32_16x16x32_bf16 v[2:5], v[172:175], v[214:217], v[2:5]
	v_mfma_f32_16x16x32_bf16 v[30:33], v[168:171], v[184:187], v[30:33]
	v_mfma_f32_16x16x32_bf16 v[26:29], v[176:179], v[184:187], v[26:29]
	v_mfma_f32_16x16x32_bf16 v[22:25], v[168:171], v[192:195], v[22:25]
	v_mfma_f32_16x16x32_bf16 v[18:21], v[176:179], v[192:195], v[18:21]
	v_mfma_f32_16x16x32_bf16 v[14:17], v[168:171], v[200:203], v[14:17]
	v_mfma_f32_16x16x32_bf16 v[10:13], v[176:179], v[200:203], v[10:13]
	v_mfma_f32_16x16x32_bf16 v[6:9], v[168:171], v[218:221], v[6:9]
	v_mfma_f32_16x16x32_bf16 v[2:5], v[176:179], v[218:221], v[2:5]
	s_setprio 0
	s_barrier
	s_add_u32 s0, s0, 0x100
	s_addc_u32 s1, s1, 0
	s_add_u32 s6, s6, 0x100
	s_addc_u32 s7, s7, 0
	s_cmp_ge_i32 s9, s76
	s_mov_b32 s4, s9
	s_cbranch_scc1 .Lin1_exit

.Lin1_exit:
	s_and_b64 vcc, exec, s[20:21]
	s_cbranch_vccz .LBB0_1145
